# cmp_gemm2: all loads issued up front, counted vmcnt, 32 back-to-back MFMAs (was load-wait-MFMA per step)
# speedup vs baseline: 1.0241x; 1.0087x over previous
; #define LAUNDER(x) asm volatile("" : "+v"(x))
; #define MFMA32(a, b, c) __builtin_amdgcn_mfma_f32_32x32x16_bf16((a), (b), (c), 0, 0, 0)
; #define WAVE_F (__builtin_amdgcn_readfirstlane(TID_F >> 6))
; __device__ __forceinline__ void cmp_gemm2(const bf16_t* hidden, const bf16_t* w2t, bf16_t* kcmp, bf16_t* vcmpT, int kv, int row0, int lane) {
;     LAUNDER(lane);
;     const int r = lane & 31, h = lane >> 5;
;     f32x16 acc[2];
; #pragma unroll
;     for (int i = 0; i < 16; ++i) { acc[0][i] = 0.f; acc[1][i] = 0.f; }
; #pragma unroll
;     for (int ks = 0; ks < 16; ++ks) {
;         const bf16x8 hf = *(const bf16x8*)(hidden + (size_t)(row0 + r) * 256 + ks * 16 + h * 8);
; #pragma unroll
;         for (int dt = 0; dt < 2; ++dt) {
;             const bf16x8 wf = *(const bf16x8*)(w2t + (size_t)(dt * 32 + r) * 256 + ks * 16 + h * 8);
;             if (kv == 0) acc[dt] = MFMA32(wf, hf, acc[dt]);
;             else         acc[dt] = MFMA32(hf, wf, acc[dt]);
;         }
;     }
; __global__ void __launch_bounds__(NTHREADS, 2) fwd_megakernel(Params p) {
;     ...
;                     asm volatile("s_waitcnt vmcnt(0)" ::: "memory");
;                     __builtin_amdgcn_fence(__ATOMIC_RELEASE, "agent");
;                     __syncthreads();
;                     __builtin_amdgcn_fence(__ATOMIC_ACQUIRE, "agent");
;                     cmp_gemm2(hid, (const bf16_t*)(wl + (kv ? W_C2V : W_C2K)), (bf16_t*)(ws + WS_R1 + R_KCMP), (bf16_t*)(ws + WS_R1 + R_VCMPT), kv, u.pm * 256 + WAVE_F * 32, LANE_F);
.LBB0_529:
	s_and_b64 s[4:5], exec, s[4:5]
	s_mov_b32 s4, 0x1980000
	v_mov_b32_e32 v1, v222
	s_waitcnt vmcnt(0)
	buffer_wbl2 sc1
	s_waitcnt vmcnt(0)
	s_barrier
	buffer_inv sc1
	s_cselect_b32 s4, s4, 0x1990000
	s_add_u32 s4, s36, s4
	v_readfirstlane_b32 s11, v1
	v_mov_b32_e32 v1, v222
	s_addc_u32 s5, s37, 0
	v_readlane_b32 s10, v252, 5
	s_ashr_i32 s11, s11, 1
	s_lshl_b32 s10, s10, 8
	s_andn2_b32 s11, s11, 31
	v_and_b32_e32 v1, 63, v1
	s_add_i32 s10, s11, s10
	s_and_b64 vcc, exec, s[6:7]
	v_and_b32_e32 v76, 31, v1
	v_ashrrev_i32_e32 v1, 5, v1
	v_or_b32_e32 v2, s10, v76
	v_ashrrev_i32_e32 v3, 31, v2
	v_lshlrev_b32_e32 v4, 3, v1
	v_lshlrev_b64 v[2:3], 9, v[2:3]
	v_ashrrev_i32_e32 v5, 31, v4
	v_lshl_add_u64 v[2:3], s[8:9], 0, v[2:3]
	v_lshlrev_b64 v[4:5], 1, v[4:5]
	v_lshl_add_u64 v[66:67], v[2:3], 0, v[4:5]
	v_lshl_add_u64 v[70:71], s[4:5], 0, v[4:5]
	v_lshlrev_b32_e32 v2, 9, v76
	v_mov_b32_e32 v3, v0
	v_lshl_add_u64 v[72:73], v[70:71], 0, v[2:3]
	v_lshlrev_b32_e32 v18, 8, v76
	v_or_b32_e32 v18, 0x2000, v18
	v_lshlrev_b32_e32 v74, 1, v18
	v_mov_b32_e32 v75, v0
	v_lshl_add_u64 v[68:69], v[70:71], 0, v[74:75]
	s_andn2_b64 s[4:5], exec, s[6:7]
	global_load_dwordx4 v[80:83], v[66:67], off
	global_load_dwordx4 v[144:147], v[72:73], off
	global_load_dwordx4 v[34:37], v[68:69], off
	global_load_dwordx4 v[84:87], v[66:67], off offset:32
	global_load_dwordx4 v[148:151], v[72:73], off offset:32
	global_load_dwordx4 v[38:41], v[68:69], off offset:32
	global_load_dwordx4 v[88:91], v[66:67], off offset:64
	global_load_dwordx4 v[152:155], v[72:73], off offset:64
	global_load_dwordx4 v[42:45], v[68:69], off offset:64
	global_load_dwordx4 v[92:95], v[66:67], off offset:96
	global_load_dwordx4 v[156:159], v[72:73], off offset:96
	global_load_dwordx4 v[46:49], v[68:69], off offset:96
	global_load_dwordx4 v[96:99], v[66:67], off offset:128
	global_load_dwordx4 v[160:163], v[72:73], off offset:128
	global_load_dwordx4 v[50:53], v[68:69], off offset:128
	global_load_dwordx4 v[100:103], v[66:67], off offset:160
	global_load_dwordx4 v[164:167], v[72:73], off offset:160
	global_load_dwordx4 v[54:57], v[68:69], off offset:160
	global_load_dwordx4 v[104:107], v[66:67], off offset:192
	global_load_dwordx4 v[168:171], v[72:73], off offset:192
	global_load_dwordx4 v[58:61], v[68:69], off offset:192
	global_load_dwordx4 v[108:111], v[66:67], off offset:224
	global_load_dwordx4 v[172:175], v[72:73], off offset:224
	global_load_dwordx4 v[62:65], v[68:69], off offset:224
	global_load_dwordx4 v[112:115], v[66:67], off offset:256
	global_load_dwordx4 v[176:179], v[72:73], off offset:256
	global_load_dwordx4 v[116:119], v[66:67], off offset:288
	global_load_dwordx4 v[184:187], v[72:73], off offset:288
	global_load_dwordx4 v[120:123], v[66:67], off offset:320
	global_load_dwordx4 v[188:191], v[72:73], off offset:320
	global_load_dwordx4 v[124:127], v[66:67], off offset:352
	global_load_dwordx4 v[192:195], v[72:73], off offset:352
	global_load_dwordx4 v[128:131], v[66:67], off offset:384
	global_load_dwordx4 v[196:199], v[72:73], off offset:384
	global_load_dwordx4 v[132:135], v[66:67], off offset:416
	global_load_dwordx4 v[200:203], v[72:73], off offset:416
	global_load_dwordx4 v[136:139], v[66:67], off offset:448
	global_load_dwordx4 v[204:207], v[72:73], off offset:448
	global_load_dwordx4 v[140:143], v[66:67], off offset:480
	global_load_dwordx4 v[208:211], v[72:73], off offset:480
	s_and_b64 vcc, exec, s[6:7]
	s_cbranch_vccz .Lc2_kv0
	s_waitcnt vmcnt(37)
	v_mfma_f32_32x32x16_bf16 v[18:33], v[80:83], v[144:147], 0
	v_mfma_f32_32x32x16_bf16 v[2:17], v[80:83], v[34:37], 0
	s_waitcnt vmcnt(34)
	v_mfma_f32_32x32x16_bf16 v[18:33], v[84:87], v[148:151], v[18:33]
	v_mfma_f32_32x32x16_bf16 v[2:17], v[84:87], v[38:41], v[2:17]
	s_waitcnt vmcnt(31)
	v_mfma_f32_32x32x16_bf16 v[18:33], v[88:91], v[152:155], v[18:33]
	v_mfma_f32_32x32x16_bf16 v[2:17], v[88:91], v[42:45], v[2:17]
	s_waitcnt vmcnt(28)
	v_mfma_f32_32x32x16_bf16 v[18:33], v[92:95], v[156:159], v[18:33]
	v_mfma_f32_32x32x16_bf16 v[2:17], v[92:95], v[46:49], v[2:17]
	s_waitcnt vmcnt(25)
	v_mfma_f32_32x32x16_bf16 v[18:33], v[96:99], v[160:163], v[18:33]
	v_mfma_f32_32x32x16_bf16 v[2:17], v[96:99], v[50:53], v[2:17]
	s_waitcnt vmcnt(22)
	v_mfma_f32_32x32x16_bf16 v[18:33], v[100:103], v[164:167], v[18:33]
	v_mfma_f32_32x32x16_bf16 v[2:17], v[100:103], v[54:57], v[2:17]
	s_waitcnt vmcnt(19)
	v_mfma_f32_32x32x16_bf16 v[18:33], v[104:107], v[168:171], v[18:33]
	v_mfma_f32_32x32x16_bf16 v[2:17], v[104:107], v[58:61], v[2:17]
	s_waitcnt vmcnt(16)
	v_mfma_f32_32x32x16_bf16 v[18:33], v[108:111], v[172:175], v[18:33]
	v_mfma_f32_32x32x16_bf16 v[2:17], v[108:111], v[62:65], v[2:17]
	global_load_dwordx4 v[144:147], v[68:69], off offset:256
	global_load_dwordx4 v[148:151], v[68:69], off offset:288
	global_load_dwordx4 v[152:155], v[68:69], off offset:320
	global_load_dwordx4 v[156:159], v[68:69], off offset:352
	global_load_dwordx4 v[160:163], v[68:69], off offset:384
	global_load_dwordx4 v[164:167], v[68:69], off offset:416
	global_load_dwordx4 v[168:171], v[68:69], off offset:448
	global_load_dwordx4 v[172:175], v[68:69], off offset:480
	s_waitcnt vmcnt(22)
	v_mfma_f32_32x32x16_bf16 v[18:33], v[112:115], v[176:179], v[18:33]
	s_waitcnt vmcnt(20)
	v_mfma_f32_32x32x16_bf16 v[18:33], v[116:119], v[184:187], v[18:33]
	s_waitcnt vmcnt(18)
	v_mfma_f32_32x32x16_bf16 v[18:33], v[120:123], v[188:191], v[18:33]
	s_waitcnt vmcnt(16)
	v_mfma_f32_32x32x16_bf16 v[18:33], v[124:127], v[192:195], v[18:33]
	s_waitcnt vmcnt(14)
	v_mfma_f32_32x32x16_bf16 v[18:33], v[128:131], v[196:199], v[18:33]
	s_waitcnt vmcnt(12)
	v_mfma_f32_32x32x16_bf16 v[18:33], v[132:135], v[200:203], v[18:33]
	s_waitcnt vmcnt(10)
	v_mfma_f32_32x32x16_bf16 v[18:33], v[136:139], v[204:207], v[18:33]
	s_waitcnt vmcnt(8)
	v_mfma_f32_32x32x16_bf16 v[18:33], v[140:143], v[208:211], v[18:33]
	s_waitcnt vmcnt(7)
	v_mfma_f32_32x32x16_bf16 v[2:17], v[112:115], v[144:147], v[2:17]
	s_waitcnt vmcnt(6)
	v_mfma_f32_32x32x16_bf16 v[2:17], v[116:119], v[148:151], v[2:17]
	s_waitcnt vmcnt(5)
	v_mfma_f32_32x32x16_bf16 v[2:17], v[120:123], v[152:155], v[2:17]
	s_waitcnt vmcnt(4)
	v_mfma_f32_32x32x16_bf16 v[2:17], v[124:127], v[156:159], v[2:17]
	s_waitcnt vmcnt(3)
	v_mfma_f32_32x32x16_bf16 v[2:17], v[128:131], v[160:163], v[2:17]
	s_waitcnt vmcnt(2)
	v_mfma_f32_32x32x16_bf16 v[2:17], v[132:135], v[164:167], v[2:17]
	s_waitcnt vmcnt(1)
	v_mfma_f32_32x32x16_bf16 v[2:17], v[136:139], v[168:171], v[2:17]
	s_waitcnt vmcnt(0)
	v_mfma_f32_32x32x16_bf16 v[2:17], v[140:143], v[172:175], v[2:17]
	s_branch .LBB0_657
; #define MFMA32(a, b, c) __builtin_amdgcn_mfma_f32_32x32x16_bf16((a), (b), (c), 0, 0, 0)
; __device__ __forceinline__ void cmp_gemm2(const bf16_t* hidden, const bf16_t* w2t, bf16_t* kcmp, bf16_t* vcmpT, int kv, int row0, int lane) {
;     ...
;     for (int ks = 0; ks < 16; ++ks) {
;         const bf16x8 hf = *(const bf16x8*)(hidden + (size_t)(row0 + r) * 256 + ks * 16 + h * 8);
; #pragma unroll
;         for (int dt = 0; dt < 2; ++dt) {
;             const bf16x8 wf = *(const bf16x8*)(w2t + (size_t)(dt * 32 + r) * 256 + ks * 16 + h * 8);
;             if (kv == 0) acc[dt] = MFMA32(wf, hf, acc[dt]);
;             else         acc[dt] = MFMA32(hf, wf, acc[dt]);
;         }
;     }
.Lc2_kv0:
	s_waitcnt vmcnt(37)
	v_mfma_f32_32x32x16_bf16 v[18:33], v[144:147], v[80:83], 0
	v_mfma_f32_32x32x16_bf16 v[2:17], v[34:37], v[80:83], 0
	s_waitcnt vmcnt(34)
	v_mfma_f32_32x32x16_bf16 v[18:33], v[148:151], v[84:87], v[18:33]
	v_mfma_f32_32x32x16_bf16 v[2:17], v[38:41], v[84:87], v[2:17]
	s_waitcnt vmcnt(31)
	v_mfma_f32_32x32x16_bf16 v[18:33], v[152:155], v[88:91], v[18:33]
	v_mfma_f32_32x32x16_bf16 v[2:17], v[42:45], v[88:91], v[2:17]
	s_waitcnt vmcnt(28)
	v_mfma_f32_32x32x16_bf16 v[18:33], v[156:159], v[92:95], v[18:33]
	v_mfma_f32_32x32x16_bf16 v[2:17], v[46:49], v[92:95], v[2:17]
	s_waitcnt vmcnt(25)
	v_mfma_f32_32x32x16_bf16 v[18:33], v[160:163], v[96:99], v[18:33]
	v_mfma_f32_32x32x16_bf16 v[2:17], v[50:53], v[96:99], v[2:17]
	s_waitcnt vmcnt(22)
	v_mfma_f32_32x32x16_bf16 v[18:33], v[164:167], v[100:103], v[18:33]
	v_mfma_f32_32x32x16_bf16 v[2:17], v[54:57], v[100:103], v[2:17]
	s_waitcnt vmcnt(19)
	v_mfma_f32_32x32x16_bf16 v[18:33], v[168:171], v[104:107], v[18:33]
	v_mfma_f32_32x32x16_bf16 v[2:17], v[58:61], v[104:107], v[2:17]
	s_waitcnt vmcnt(16)
	v_mfma_f32_32x32x16_bf16 v[18:33], v[172:175], v[108:111], v[18:33]
	v_mfma_f32_32x32x16_bf16 v[2:17], v[62:65], v[108:111], v[2:17]
	global_load_dwordx4 v[144:147], v[68:69], off offset:256
	global_load_dwordx4 v[148:151], v[68:69], off offset:288
	global_load_dwordx4 v[152:155], v[68:69], off offset:320
	global_load_dwordx4 v[156:159], v[68:69], off offset:352
	global_load_dwordx4 v[160:163], v[68:69], off offset:384
	global_load_dwordx4 v[164:167], v[68:69], off offset:416
	global_load_dwordx4 v[168:171], v[68:69], off offset:448
	global_load_dwordx4 v[172:175], v[68:69], off offset:480
	s_waitcnt vmcnt(22)
	v_mfma_f32_32x32x16_bf16 v[18:33], v[176:179], v[112:115], v[18:33]
	s_waitcnt vmcnt(20)
	v_mfma_f32_32x32x16_bf16 v[18:33], v[184:187], v[116:119], v[18:33]
	s_waitcnt vmcnt(18)
	v_mfma_f32_32x32x16_bf16 v[18:33], v[188:191], v[120:123], v[18:33]
	s_waitcnt vmcnt(16)
	v_mfma_f32_32x32x16_bf16 v[18:33], v[192:195], v[124:127], v[18:33]
	s_waitcnt vmcnt(14)
	v_mfma_f32_32x32x16_bf16 v[18:33], v[196:199], v[128:131], v[18:33]
	s_waitcnt vmcnt(12)
	v_mfma_f32_32x32x16_bf16 v[18:33], v[200:203], v[132:135], v[18:33]
	s_waitcnt vmcnt(10)
	v_mfma_f32_32x32x16_bf16 v[18:33], v[204:207], v[136:139], v[18:33]
	s_waitcnt vmcnt(8)
	v_mfma_f32_32x32x16_bf16 v[18:33], v[208:211], v[140:143], v[18:33]
	s_waitcnt vmcnt(7)
	v_mfma_f32_32x32x16_bf16 v[2:17], v[144:147], v[112:115], v[2:17]
	s_waitcnt vmcnt(6)
	v_mfma_f32_32x32x16_bf16 v[2:17], v[148:151], v[116:119], v[2:17]
	s_waitcnt vmcnt(5)
	v_mfma_f32_32x32x16_bf16 v[2:17], v[152:155], v[120:123], v[2:17]
	s_waitcnt vmcnt(4)
	v_mfma_f32_32x32x16_bf16 v[2:17], v[156:159], v[124:127], v[2:17]
	s_waitcnt vmcnt(3)
	v_mfma_f32_32x32x16_bf16 v[2:17], v[160:163], v[128:131], v[2:17]
	s_waitcnt vmcnt(2)
	v_mfma_f32_32x32x16_bf16 v[2:17], v[164:167], v[132:135], v[2:17]
	s_waitcnt vmcnt(1)
	v_mfma_f32_32x32x16_bf16 v[2:17], v[168:171], v[136:139], v[2:17]
	s_waitcnt vmcnt(0)
	v_mfma_f32_32x32x16_bf16 v[2:17], v[172:175], v[140:143], v[2:17]

; __device__ __forceinline__ float fast_exp2(float x) { return __builtin_amdgcn_exp2f(x); }
; __device__ __forceinline__ float xhalf_max(float x) { auto t = __builtin_amdgcn_permlane32_swap(__float_as_uint(x), __float_as_uint(x), false, false); return fmaxf(__uint_as_float(t[0]), __uint_as_float(t[1])); }
; __device__ __forceinline__ float xhalf_sum(float x) { auto t = __builtin_amdgcn_permlane32_swap(__float_as_uint(x), __float_as_uint(x), false, false); return __uint_as_float(t[0]) + __uint_as_float(t[1]); }
; __device__ __forceinline__ void nsa_unit(const Params& p, int bg, int jq, LAS unsigned char* lds, int wave, int lane, bool build_lut) {
;     ...
;             float mx = s[0];
; #pragma unroll
;             for (int i = 1; i < 16; ++i) mx = fmaxf(mx, s[i]);
;             mx = xhalf_max(mx);
;             const float mnew = fmaxf(m, mx);
;             float ps = 0.f;
; #pragma unroll
;             for (int i = 0; i < 16; ++i) ps += fast_exp2(s[i] - mnew);
;             ps = xhalf_sum(ps);
;             l = l * fast_exp2(m - mnew) + ps; m = mnew;
.LBB0_1091:
	v_max3_f32 v18, v2, v3, v4
	v_max3_f32 v19, v5, v6, v7
	v_max3_f32 v20, v8, v9, v10
	v_max3_f32 v21, v11, v12, v13
	v_max3_f32 v18, v18, v14, v15
	v_max3_f32 v19, v19, v16, v17
	v_max3_f32 v18, v18, v20, v21
	v_max_f32_e32 v18, v18, v19
	v_mov_b32_e32 v19, v18
	s_nop 1
	v_permlane32_swap_b32_e32 v18, v19
	v_max3_f32 v85, v84, v18, v19
	v_pk_add_f32 v[2:3], v[2:3], v[84:85] op_sel:[0,1] op_sel_hi:[1,1] neg_lo:[0,1] neg_hi:[0,1]
	v_pk_add_f32 v[4:5], v[4:5], v[84:85] op_sel:[0,1] op_sel_hi:[1,1] neg_lo:[0,1] neg_hi:[0,1]
	v_pk_add_f32 v[6:7], v[6:7], v[84:85] op_sel:[0,1] op_sel_hi:[1,1] neg_lo:[0,1] neg_hi:[0,1]
	v_pk_add_f32 v[8:9], v[8:9], v[84:85] op_sel:[0,1] op_sel_hi:[1,1] neg_lo:[0,1] neg_hi:[0,1]
	v_pk_add_f32 v[10:11], v[10:11], v[84:85] op_sel:[0,1] op_sel_hi:[1,1] neg_lo:[0,1] neg_hi:[0,1]
	v_pk_add_f32 v[12:13], v[12:13], v[84:85] op_sel:[0,1] op_sel_hi:[1,1] neg_lo:[0,1] neg_hi:[0,1]
	v_pk_add_f32 v[14:15], v[14:15], v[84:85] op_sel:[0,1] op_sel_hi:[1,1] neg_lo:[0,1] neg_hi:[0,1]
	v_pk_add_f32 v[16:17], v[16:17], v[84:85] op_sel:[0,1] op_sel_hi:[1,1] neg_lo:[0,1] neg_hi:[0,1]
	v_sub_f32_e32 v18, v84, v85
	v_exp_f32_e32 v2, v2
	v_exp_f32_e32 v3, v3
	v_exp_f32_e32 v4, v4
	v_exp_f32_e32 v5, v5
	v_exp_f32_e32 v6, v6
	v_exp_f32_e32 v7, v7
	v_exp_f32_e32 v8, v8
	v_exp_f32_e32 v9, v9
	v_exp_f32_e32 v10, v10
	v_exp_f32_e32 v11, v11
	v_exp_f32_e32 v12, v12
	v_exp_f32_e32 v13, v13
	v_exp_f32_e32 v14, v14
	v_exp_f32_e32 v15, v15
	v_exp_f32_e32 v16, v16
	v_exp_f32_e32 v17, v17
	v_exp_f32_e32 v18, v18
	v_pk_add_f32 v[20:21], v[2:3], v[4:5]
	v_pk_add_f32 v[22:23], v[6:7], v[8:9]
	v_pk_add_f32 v[24:25], v[10:11], v[12:13]
	v_pk_add_f32 v[26:27], v[14:15], v[16:17]
	v_pk_add_f32 v[20:21], v[20:21], v[22:23]
	v_pk_add_f32 v[24:25], v[24:25], v[26:27]
	v_pk_add_f32 v[20:21], v[20:21], v[24:25]
	v_add_f32_e32 v2, v20, v21
	v_mov_b32_e32 v3, v2
	s_nop 1
	v_permlane32_swap_b32_e32 v2, v3
	v_add_f32_e32 v86, v2, v3
	s_add_i32 s19, s19, 1
	s_addk_i32 s13, 0xfe00
	v_fmac_f32_e32 v86, v83, v18
	v_add_u32_e32 v82, 0xfffffe00, v82
	s_cmp_eq_u32 s12, s19
	v_lshl_add_u64 v[64:65], v[64:65], 0, s[84:85]
	s_cbranch_scc0 .LBB0_1053
	s_branch .LBB0_1093

; __device__ __forceinline__ float fast_exp2(float x) { return __builtin_amdgcn_exp2f(x); }
; __device__ __forceinline__ void nsa_unit(const Params& p, int bg, int jq, LAS unsigned char* lds, int wave, int lane, bool build_lut) {
;     ...
;             if (fast) {
; #pragma unroll
;                 for (int i = 0; i < 16; ++i) s[i] = fast_exp2(s[i] - c2f);
.LBB0_1131:
	s_and_b64 vcc, exec, s[18:19]
	s_cbranch_vccz .LBB0_1133
	s_nop 8
	v_pk_add_f32 v[34:35], v[34:35], v[120:121] op_sel_hi:[1,0] neg_lo:[0,1] neg_hi:[0,1]
	v_pk_add_f32 v[36:37], v[36:37], v[120:121] op_sel_hi:[1,0] neg_lo:[0,1] neg_hi:[0,1]
	v_pk_add_f32 v[38:39], v[38:39], v[120:121] op_sel_hi:[1,0] neg_lo:[0,1] neg_hi:[0,1]
	v_pk_add_f32 v[40:41], v[40:41], v[120:121] op_sel_hi:[1,0] neg_lo:[0,1] neg_hi:[0,1]
	v_pk_add_f32 v[42:43], v[42:43], v[120:121] op_sel_hi:[1,0] neg_lo:[0,1] neg_hi:[0,1]
	v_pk_add_f32 v[44:45], v[44:45], v[120:121] op_sel_hi:[1,0] neg_lo:[0,1] neg_hi:[0,1]
	v_pk_add_f32 v[46:47], v[46:47], v[120:121] op_sel_hi:[1,0] neg_lo:[0,1] neg_hi:[0,1]
	v_pk_add_f32 v[48:49], v[48:49], v[120:121] op_sel_hi:[1,0] neg_lo:[0,1] neg_hi:[0,1]
	v_exp_f32_e32 v50, v34
	v_exp_f32_e32 v51, v35
	v_exp_f32_e32 v52, v36
	v_exp_f32_e32 v53, v37
	v_exp_f32_e32 v54, v38
	v_exp_f32_e32 v55, v39
	v_exp_f32_e32 v56, v40
	v_exp_f32_e32 v57, v41
	v_exp_f32_e32 v58, v42
	v_exp_f32_e32 v59, v43
	v_exp_f32_e32 v60, v44
	v_exp_f32_e32 v61, v45
	v_exp_f32_e32 v62, v46
	v_exp_f32_e32 v63, v47
	v_exp_f32_e32 v64, v48
	v_mov_b32_e32 v65, v49

; template <int STRIDE> __device__ __forceinline__ void score_tile(f32x16& s, int dl, int dmax, bool lane_ok, bool fast, float lutfar, const LAS float* lutr) {
;     if (fast) {
; #pragma unroll
;         for (int i = 0; i < 16; ++i) s[i] = lane_ok ? (s[i] + lutfar) : NEG_INF;
;     } else {
; #pragma unroll
;         for (int i = 0; i < 16; ++i) {
;             const int d = dl - STRIDE * ((i & 3) + 8 * (i >> 2));
;             const bool ok = lane_ok && d >= 0 && d < dmax;
;             const int di = min(max(d, 0), 128);
;             s[i] = ok ? (s[i] + lutr[di]) : NEG_INF;
;         }
;     }
; }
; __device__ __forceinline__ void pv_tile(f32x16& o0, f32x16& o1, const f32x16& pr, const bf16x8 (&vf)[2][2]) {
; #pragma unroll
;     for (int s = 0; s < 2; ++s) {
;         u32x4 pk; pk.x = cvt_pk_bf16(pr[8 * s], pr[8 * s + 1]); pk.y = cvt_pk_bf16(pr[8 * s + 2], pr[8 * s + 3]); pk.z = cvt_pk_bf16(pr[8 * s + 4], pr[8 * s + 5]); pk.w = cvt_pk_bf16(pr[8 * s + 6], pr[8 * s + 7]);
;         const bf16x8 pb = __builtin_bit_cast(bf16x8, pk);
;         o0 = MFMA32(vf[0][s], pb, o0);
;         o1 = MFMA32(vf[1][s], pb, o1);
;     }
; }
; template <bool FAST> __device__ __forceinline__ void online_step(f32x16& s, float bias, bool lane_ok, float& m, float& l, f32x16& o0, f32x16& o1, const bf16x8 (&vf)[2][2]) {
;     float mx = fmaxf(fmaxf(fmaxf(s[0], s[1]), fmaxf(s[2], s[3])), fmaxf(fmaxf(s[4], s[5]), fmaxf(s[6], s[7])));
;     mx = fmaxf(mx, fmaxf(fmaxf(fmaxf(s[8], s[9]), fmaxf(s[10], s[11])), fmaxf(fmaxf(s[12], s[13]), fmaxf(s[14], s[15]))));
;     if (FAST) { mx += bias; mx = lane_ok ? mx : NEG_INF; }
;     mx = xhalf_max(mx);
; __device__ __forceinline__ void nsa_unit(const Params& p, int bg, int jq, LAS unsigned char* lds, int wave, int lane, bool build_lut) {
;     ...
;         for (int T = T0; T <= T1; ++T) {
; #pragma unroll
;             for (int ks = 0; ks < 4; ++ks) kf[ks] = kn[ks];
;             load_v(vf, vwT + (size_t)T * 2048, lane);
;             if (T < T1) load_k(kn, kwb + (size_t)(32 * (T + 1)) * 64, lane);
;             const int base = 32 * T;
;             f32x16 s = qk_tile(kf, qf);
;             if (((tq0 - base - 31) >= 128) && ((tq0 + 7 - base) < 512)) online_step<true>(s, lutfar, true, m, l, o0, o1, vf);
;             else { score_tile<1>(s, tq - base - 4 * h, 512, true, false, lutfar, lutr); online_step<false>(s, 0.f, true, m, l, o0, o1, vf); }
.LBB0_1284:
	s_waitcnt lgkmcnt(0)
	v_mfma_f32_32x32x16_bf16 v[48:63], v[48:51], v[140:143], 0
	s_add_i32 s5, s13, -7
	s_cmpk_gt_i32 s5, 0x9e
	s_cselect_b64 s[10:11], -1, 0
	s_cmpk_lt_i32 s13, 0x200
	s_cselect_b64 s[16:17], -1, 0
	s_and_b64 s[16:17], s[10:11], s[16:17]
	s_mov_b64 s[10:11], -1
	v_mfma_f32_32x32x16_bf16 v[48:63], v[172:175], v[136:139], v[48:63]
	s_andn2_b64 vcc, exec, s[16:17]
	v_mfma_f32_32x32x16_bf16 v[48:63], v[168:171], v[132:135], v[48:63]
	v_mfma_f32_32x32x16_bf16 v[48:63], v[164:167], v[128:131], v[48:63]
	s_cbranch_vccz .LBB0_1320
	v_add_u32_e32 v64, s13, v180
	v_mov_b32_e32 v240, 0xff800000
	v_add_u32_e32 v164, -7, v64
	v_min_u32_e32 v164, 0x80, v164
	v_lshl_add_u32 v164, v164, 2, v231
	ds_read_b32 v164, v164 offset:8448
	v_add_u32_e32 v1, -8, v64
	v_min_u32_e32 v1, 0x80, v1
	v_lshl_add_u32 v1, v1, 2, v231
	ds_read_b32 v1, v1 offset:8448
	v_add_u32_e32 v166, -9, v64
	v_min_u32_e32 v166, 0x80, v166
	v_lshl_add_u32 v166, v166, 2, v231
	ds_read_b32 v166, v166 offset:8448
	v_add_u32_e32 v165, -10, v64
	v_min_u32_e32 v165, 0x80, v165
	v_lshl_add_u32 v165, v165, 2, v231
	ds_read_b32 v165, v165 offset:8448
	v_add_u32_e32 v168, -15, v64
	v_min_u32_e32 v168, 0x80, v168
	v_lshl_add_u32 v168, v168, 2, v231
	ds_read_b32 v168, v168 offset:8448
	v_add_u32_e32 v167, -16, v64
	v_min_u32_e32 v167, 0x80, v167
	v_lshl_add_u32 v167, v167, 2, v231
	ds_read_b32 v167, v167 offset:8448
	v_subrev_u32_e32 v170, 17, v64
	v_min_u32_e32 v170, 0x80, v170
	v_lshl_add_u32 v170, v170, 2, v231
	ds_read_b32 v170, v170 offset:8448
	v_subrev_u32_e32 v169, 18, v64
	v_min_u32_e32 v169, 0x80, v169
	v_lshl_add_u32 v169, v169, 2, v231
	ds_read_b32 v169, v169 offset:8448
	v_subrev_u32_e32 v172, 23, v64
	v_min_u32_e32 v172, 0x80, v172
	v_lshl_add_u32 v172, v172, 2, v231
	ds_read_b32 v172, v172 offset:8448
	v_subrev_u32_e32 v171, 24, v64
	v_min_u32_e32 v171, 0x80, v171
	v_lshl_add_u32 v171, v171, 2, v231
	ds_read_b32 v171, v171 offset:8448
	v_subrev_u32_e32 v174, 25, v64
	v_min_u32_e32 v174, 0x80, v174
	v_lshl_add_u32 v174, v174, 2, v231
	ds_read_b32 v174, v174 offset:8448
	v_subrev_u32_e32 v173, 26, v64
	v_min_u32_e32 v173, 0x80, v173
	v_lshl_add_u32 v173, v173, 2, v231
	ds_read_b32 v173, v173 offset:8448
	v_subrev_u32_e32 v234, 31, v64
	v_min_u32_e32 v234, 0x80, v234
	v_lshl_add_u32 v234, v234, 2, v231
	ds_read_b32 v234, v234 offset:8448
	v_subrev_u32_e32 v175, 32, v64
	v_min_u32_e32 v175, 0x80, v175
	v_lshl_add_u32 v175, v175, 2, v231
	ds_read_b32 v175, v175 offset:8448
	v_subrev_u32_e32 v235, 33, v64
	v_min_u32_e32 v235, 0x80, v235
	v_lshl_add_u32 v235, v235, 2, v231
	ds_read_b32 v235, v235 offset:8448
	v_subrev_u32_e32 v232, 34, v64
	v_min_u32_e32 v232, 0x80, v232
	v_lshl_add_u32 v232, v232, 2, v231
	ds_read_b32 v232, v232 offset:8448
	v_add_u32_e32 v238, -7, v64
	s_waitcnt lgkmcnt(15)
	v_cmp_gt_u32_e32 vcc, s77, v238
	v_add_u32_e32 v239, -8, v64
	v_add_f32_e32 v164, v48, v164
	v_cndmask_b32_e32 v164, v240, v164, vcc
	v_cmp_gt_u32_e32 vcc, s77, v239
	v_add_u32_e32 v238, -9, v64
	s_waitcnt lgkmcnt(14)
	v_add_f32_e32 v1, v49, v1
	v_cndmask_b32_e32 v1, v240, v1, vcc
	v_cmp_gt_u32_e32 vcc, s77, v238
	v_add_u32_e32 v239, -10, v64
	s_waitcnt lgkmcnt(13)
	v_add_f32_e32 v166, v50, v166
	v_cndmask_b32_e32 v166, v240, v166, vcc
	v_cmp_gt_u32_e32 vcc, s77, v239
	v_add_u32_e32 v238, -15, v64
	s_waitcnt lgkmcnt(12)
	v_add_f32_e32 v165, v51, v165
	v_cndmask_b32_e32 v165, v240, v165, vcc
	v_cmp_gt_u32_e32 vcc, s77, v238
	v_add_u32_e32 v239, -16, v64
	s_waitcnt lgkmcnt(11)
	v_add_f32_e32 v168, v52, v168
	v_cndmask_b32_e32 v168, v240, v168, vcc
	v_cmp_gt_u32_e32 vcc, s77, v239
	v_subrev_u32_e32 v238, 17, v64
	s_waitcnt lgkmcnt(10)
	v_add_f32_e32 v167, v53, v167
	v_cndmask_b32_e32 v167, v240, v167, vcc
	v_cmp_gt_u32_e32 vcc, s77, v238
	v_subrev_u32_e32 v239, 18, v64
	s_waitcnt lgkmcnt(9)
	v_add_f32_e32 v170, v54, v170
	v_cndmask_b32_e32 v170, v240, v170, vcc
	v_cmp_gt_u32_e32 vcc, s77, v239
	v_subrev_u32_e32 v238, 23, v64
	s_waitcnt lgkmcnt(8)
	v_add_f32_e32 v169, v55, v169
	v_cndmask_b32_e32 v169, v240, v169, vcc
	v_cmp_gt_u32_e32 vcc, s77, v238
	v_subrev_u32_e32 v239, 24, v64
	s_waitcnt lgkmcnt(7)
	v_add_f32_e32 v172, v56, v172
	v_cndmask_b32_e32 v172, v240, v172, vcc
	v_cmp_gt_u32_e32 vcc, s77, v239
	v_subrev_u32_e32 v238, 25, v64
	s_waitcnt lgkmcnt(6)
	v_add_f32_e32 v171, v57, v171
	v_cndmask_b32_e32 v171, v240, v171, vcc
	v_cmp_gt_u32_e32 vcc, s77, v238
	v_subrev_u32_e32 v239, 26, v64
	s_waitcnt lgkmcnt(5)
	v_add_f32_e32 v174, v58, v174
	v_cndmask_b32_e32 v174, v240, v174, vcc
	v_cmp_gt_u32_e32 vcc, s77, v239
	v_subrev_u32_e32 v238, 31, v64
	s_waitcnt lgkmcnt(4)
	v_add_f32_e32 v173, v59, v173
	v_cndmask_b32_e32 v173, v240, v173, vcc
	v_cmp_gt_u32_e32 vcc, s77, v238
	v_subrev_u32_e32 v239, 32, v64
	s_waitcnt lgkmcnt(3)
	v_add_f32_e32 v234, v60, v234
	v_cndmask_b32_e32 v234, v240, v234, vcc
	v_cmp_gt_u32_e32 vcc, s77, v239
	v_subrev_u32_e32 v238, 33, v64
	s_waitcnt lgkmcnt(2)
	v_add_f32_e32 v175, v61, v175
	v_cndmask_b32_e32 v175, v240, v175, vcc
	v_cmp_gt_u32_e32 vcc, s77, v238
	v_subrev_u32_e32 v239, 34, v64
	s_waitcnt lgkmcnt(1)
	v_add_f32_e32 v235, v62, v235
	v_cndmask_b32_e32 v235, v240, v235, vcc
	v_cmp_gt_u32_e32 vcc, s77, v239
	s_nop 0
	s_waitcnt lgkmcnt(0)
	v_add_f32_e32 v232, v63, v232
	v_cndmask_b32_e32 v232, v240, v232, vcc
	v_max3_f32 v64, v164, v1, v166
	v_max3_f32 v65, v165, v168, v167
	v_max3_f32 v66, v170, v169, v172
	v_max3_f32 v67, v171, v174, v173
	v_max3_f32 v68, v234, v175, v235
	v_max3_f32 v64, v64, v65, v232
	v_max3_f32 v64, v64, v66, v67
	v_max_f32_e32 v64, v64, v68
	v_mov_b32_e32 v65, v64
	s_nop 1
	v_permlane32_swap_b32_e32 v64, v65
	v_max_f32_e32 v237, v64, v65
	v_add_f32_e32 v64, 0x41000000, v185
	v_cmp_gt_f32_e32 vcc, v237, v64
	v_mov_b32_e32 v233, v185
	v_mov_b32_e32 v236, v189
	s_cbranch_vccz .LBB0_1319
	v_cndmask_b32_e32 v233, v185, v237, vcc
	v_sub_f32_e32 v64, v185, v233
	v_exp_f32_e32 v80, v64
	s_nop 0
	v_mul_f32_e32 v236, v189, v80
	v_pk_mul_f32 v[30:31], v[30:31], v[80:81] op_sel_hi:[1,0]
	v_pk_mul_f32 v[28:29], v[28:29], v[80:81] op_sel_hi:[1,0]
	v_pk_mul_f32 v[26:27], v[26:27], v[80:81] op_sel_hi:[1,0]
	v_pk_mul_f32 v[24:25], v[24:25], v[80:81] op_sel_hi:[1,0]
	v_pk_mul_f32 v[22:23], v[22:23], v[80:81] op_sel_hi:[1,0]
	v_pk_mul_f32 v[20:21], v[20:21], v[80:81] op_sel_hi:[1,0]
	v_pk_mul_f32 v[18:19], v[18:19], v[80:81] op_sel_hi:[1,0]
	v_pk_mul_f32 v[16:17], v[16:17], v[80:81] op_sel_hi:[1,0]
	v_pk_mul_f32 v[46:47], v[46:47], v[80:81] op_sel_hi:[1,0]
	v_pk_mul_f32 v[44:45], v[44:45], v[80:81] op_sel_hi:[1,0]
	v_pk_mul_f32 v[42:43], v[42:43], v[80:81] op_sel_hi:[1,0]
	v_pk_mul_f32 v[40:41], v[40:41], v[80:81] op_sel_hi:[1,0]
	v_pk_mul_f32 v[38:39], v[38:39], v[80:81] op_sel_hi:[1,0]
	v_pk_mul_f32 v[36:37], v[36:37], v[80:81] op_sel_hi:[1,0]
	v_pk_mul_f32 v[34:35], v[34:35], v[80:81] op_sel_hi:[1,0]
	v_pk_mul_f32 v[32:33], v[32:33], v[80:81] op_sel_hi:[1,0]
; __device__ __forceinline__ unsigned cvt_pk_bf16(float lo, float hi) { unsigned r; asm volatile("v_cvt_pk_bf16_f32 %0, %1, %2" : "=v"(r) : "v"(lo), "v"(hi)); return r; }
; __device__ __forceinline__ float fast_exp2(float x) { return __builtin_amdgcn_exp2f(x); }
; __device__ __forceinline__ float xhalf_max(float x) { auto t = __builtin_amdgcn_permlane32_swap(__float_as_uint(x), __float_as_uint(x), false, false); return fmaxf(__uint_as_float(t[0]), __uint_as_float(t[1])); }
; __device__ __forceinline__ float xhalf_sum(float x) { auto t = __builtin_amdgcn_permlane32_swap(__float_as_uint(x), __float_as_uint(x), false, false); return __uint_as_float(t[0]) + __uint_as_float(t[1]); }
; #define MFMA32(a, b, c) __builtin_amdgcn_mfma_f32_32x32x16_bf16((a), (b), (c), 0, 0, 0)
; __device__ __forceinline__ void pv_tile(f32x16& o0, f32x16& o1, const f32x16& pr, const bf16x8 (&vf)[2][2]) {
; #pragma unroll
;     for (int s = 0; s < 2; ++s) {
;         u32x4 pk; pk.x = cvt_pk_bf16(pr[8 * s], pr[8 * s + 1]); pk.y = cvt_pk_bf16(pr[8 * s + 2], pr[8 * s + 3]); pk.z = cvt_pk_bf16(pr[8 * s + 4], pr[8 * s + 5]); pk.w = cvt_pk_bf16(pr[8 * s + 6], pr[8 * s + 7]);
;         const bf16x8 pb = __builtin_bit_cast(bf16x8, pk);
;         o0 = MFMA32(vf[0][s], pb, o0);
;         o1 = MFMA32(vf[1][s], pb, o1);
;     }
; }
; template <bool FAST> __device__ __forceinline__ void online_step(f32x16& s, float bias, bool lane_ok, float& m, float& l, f32x16& o0, f32x16& o1, const bf16x8 (&vf)[2][2]) {
;     float mx = fmaxf(fmaxf(fmaxf(s[0], s[1]), fmaxf(s[2], s[3])), fmaxf(fmaxf(s[4], s[5]), fmaxf(s[6], s[7])));
;     mx = fmaxf(mx, fmaxf(fmaxf(fmaxf(s[8], s[9]), fmaxf(s[10], s[11])), fmaxf(fmaxf(s[12], s[13]), fmaxf(s[14], s[15]))));
;     if (FAST) { mx += bias; mx = lane_ok ? mx : NEG_INF; }
;     mx = xhalf_max(mx);
;     if (__any(mx > m + 8.0f)) {
;         const float mnew = (mx > m + 8.0f) ? mx : m;
;         const float alpha = fast_exp2(m - mnew);
;         l *= alpha; m = mnew;
; #pragma unroll
;         for (int i = 0; i < 16; ++i) { o0[i] *= alpha; o1[i] *= alpha; }
;     ...
;     const float c = FAST ? (lane_ok ? (m - bias) : __builtin_inff()) : m;
;     float ps = 0.f;
; #pragma unroll
;     for (int i = 0; i < 16; ++i) { s[i] = fast_exp2(s[i] - c); ps += s[i]; }
;     ps = xhalf_sum(ps);
;     l += ps;
;     pv_tile(o0, o1, s, vf);
.LBB0_1319:
	v_sub_f32_e32 v164, v164, v233
	v_exp_f32_e32 v164, v164
	v_sub_f32_e32 v1, v1, v233
	v_exp_f32_e32 v1, v1
	v_sub_f32_e32 v166, v166, v233
	v_exp_f32_e32 v166, v166
	v_sub_f32_e32 v165, v165, v233
	v_exp_f32_e32 v165, v165
	v_sub_f32_e32 v168, v168, v233
	v_add_f32_e32 v237, 0, v164
	v_exp_f32_e32 v168, v168
	v_sub_f32_e32 v167, v167, v233
	v_add_f32_e32 v237, v1, v237
	v_exp_f32_e32 v167, v167
	v_add_f32_e32 v237, v166, v237
	v_sub_f32_e32 v170, v170, v233
	v_add_f32_e32 v237, v165, v237
	v_exp_f32_e32 v170, v170
	v_sub_f32_e32 v169, v169, v233
	v_add_f32_e32 v237, v168, v237
	v_exp_f32_e32 v169, v169
	v_sub_f32_e32 v172, v172, v233
	v_add_f32_e32 v237, v167, v237
	v_exp_f32_e32 v172, v172
	v_sub_f32_e32 v171, v171, v233
	v_cvt_pk_bf16_f32 v164, v164, v1
	v_cvt_pk_bf16_f32 v165, v166, v165
	v_cvt_pk_bf16_f32 v166, v168, v167
	v_cvt_pk_bf16_f32 v167, v170, v169
	v_exp_f32_e32 v171, v171
	s_waitcnt vmcnt(3)
	v_mfma_f32_32x32x16_bf16 v[16:31], v[160:163], v[164:167], v[16:31]
	v_sub_f32_e32 v174, v174, v233
	v_add_f32_e32 v237, v170, v237
	v_exp_f32_e32 v174, v174
	v_sub_f32_e32 v173, v173, v233
	v_add_f32_e32 v237, v169, v237
	v_exp_f32_e32 v173, v173
	v_sub_f32_e32 v234, v234, v233
	s_waitcnt vmcnt(1)
	v_mfma_f32_32x32x16_bf16 v[32:47], v[156:159], v[164:167], v[32:47]
	v_add_f32_e32 v237, v172, v237
	v_exp_f32_e32 v234, v234
	v_sub_f32_e32 v1, v175, v233
	v_add_f32_e32 v237, v171, v237
	v_exp_f32_e32 v1, v1
	v_sub_f32_e32 v169, v235, v233
	v_add_f32_e32 v168, v174, v237
	v_exp_f32_e32 v169, v169
	v_sub_f32_e32 v164, v232, v233
	v_add_f32_e32 v168, v173, v168
	v_exp_f32_e32 v170, v164
	v_add_f32_e32 v168, v234, v168
	v_cvt_pk_bf16_f32 v164, v172, v171
	v_cvt_pk_bf16_f32 v165, v174, v173
	v_cvt_pk_bf16_f32 v166, v234, v1
	v_cvt_pk_bf16_f32 v167, v169, v170
	v_add_f32_e32 v168, v1, v168
	v_mfma_f32_32x32x16_bf16 v[16:31], v[152:155], v[164:167], v[16:31]
	v_add_f32_e32 v1, v169, v168
	v_add_f32_e32 v1, v170, v1
	v_mov_b32_e32 v168, v1
	s_nop 1
	v_permlane32_swap_b32_e32 v1, v168
	v_add_f32_e32 v1, v1, v168
	v_add_f32_e32 v232, v236, v1
	s_waitcnt vmcnt(0)
	v_mfma_f32_32x32x16_bf16 v[32:47], v[148:151], v[164:167], v[32:47]
	s_mov_b64 s[10:11], 0
.LBB0_1320:
	s_and_b64 vcc, exec, s[10:11]
	s_cbranch_vccz .LBB0_1324
	s_nop 8
	v_max3_f32 v1, v48, v49, v50
	v_max3_f32 v64, v51, v52, v53
	v_max3_f32 v65, v54, v55, v56
	v_max3_f32 v66, v57, v58, v59
	v_max3_f32 v67, v60, v61, v62
	v_max3_f32 v1, v1, v64, v63
	v_max3_f32 v1, v1, v65, v66
	v_max_f32_e32 v1, v1, v67
	v_add_f32_e32 v1, v184, v1
	v_mov_b32_e32 v64, v1
	s_nop 1
	v_permlane32_swap_b32_e32 v1, v64
	v_max_f32_e32 v1, v1, v64
	v_add_f32_e32 v64, 0x41000000, v185
	v_cmp_gt_f32_e32 vcc, v1, v64
	s_cbranch_vccz .LBB0_1323
	s_nop 0
	v_cndmask_b32_e32 v1, v185, v1, vcc
	v_sub_f32_e32 v64, v185, v1
	v_exp_f32_e32 v64, v64
	v_mov_b32_e32 v185, v1
	v_mul_f32_e32 v189, v189, v64
	v_pk_mul_f32 v[30:31], v[30:31], v[64:65] op_sel_hi:[1,0]
	v_pk_mul_f32 v[28:29], v[28:29], v[64:65] op_sel_hi:[1,0]
	v_pk_mul_f32 v[26:27], v[26:27], v[64:65] op_sel_hi:[1,0]
	v_pk_mul_f32 v[24:25], v[24:25], v[64:65] op_sel_hi:[1,0]
	v_pk_mul_f32 v[22:23], v[22:23], v[64:65] op_sel_hi:[1,0]
	v_pk_mul_f32 v[20:21], v[20:21], v[64:65] op_sel_hi:[1,0]
	v_pk_mul_f32 v[18:19], v[18:19], v[64:65] op_sel_hi:[1,0]
	v_pk_mul_f32 v[16:17], v[16:17], v[64:65] op_sel_hi:[1,0]
	v_pk_mul_f32 v[46:47], v[46:47], v[64:65] op_sel_hi:[1,0]
	v_pk_mul_f32 v[44:45], v[44:45], v[64:65] op_sel_hi:[1,0]
	v_pk_mul_f32 v[42:43], v[42:43], v[64:65] op_sel_hi:[1,0]
	v_pk_mul_f32 v[40:41], v[40:41], v[64:65] op_sel_hi:[1,0]
	v_pk_mul_f32 v[38:39], v[38:39], v[64:65] op_sel_hi:[1,0]
	v_pk_mul_f32 v[36:37], v[36:37], v[64:65] op_sel_hi:[1,0]
	v_pk_mul_f32 v[34:35], v[34:35], v[64:65] op_sel_hi:[1,0]
	v_pk_mul_f32 v[32:33], v[32:33], v[64:65] op_sel_hi:[1,0]
; __device__ __forceinline__ float fast_exp2(float x) { return __builtin_amdgcn_exp2f(x); }
; __device__ __forceinline__ float xhalf_sum(float x) { auto t = __builtin_amdgcn_permlane32_swap(__float_as_uint(x), __float_as_uint(x), false, false); return __uint_as_float(t[0]) + __uint_as_float(t[1]); }
; template <bool FAST> __device__ __forceinline__ void online_step(f32x16& s, float bias, bool lane_ok, float& m, float& l, f32x16& o0, f32x16& o1, const bf16x8 (&vf)[2][2]) {
;     ...
;     const float c = FAST ? (lane_ok ? (m - bias) : __builtin_inff()) : m;
;     float ps = 0.f;
; #pragma unroll
;     for (int i = 0; i < 16; ++i) { s[i] = fast_exp2(s[i] - c); ps += s[i]; }
;     ps = xhalf_sum(ps);
;     l += ps;
;     pv_tile(o0, o1, s, vf);
; __device__ __forceinline__ void nsa_unit(const Params& p, int bg, int jq, LAS unsigned char* lds, int wave, int lane, bool build_lut) {
;     ...
;         for (int T = T0; T <= T1; ++T) {
; #pragma unroll
;             for (int ks = 0; ks < 4; ++ks) kf[ks] = kn[ks];
;             load_v(vf, vwT + (size_t)T * 2048, lane);
;             if (T < T1) load_k(kn, kwb + (size_t)(32 * (T + 1)) * 64, lane);
;             const int base = 32 * T;
;             f32x16 s = qk_tile(kf, qf);
;             if (((tq0 - base - 31) >= 128) && ((tq0 + 7 - base) < 512)) online_step<true>(s, lutfar, true, m, l, o0, o1, vf);
;             else { score_tile<1>(s, tq - base - 4 * h, 512, true, false, lutfar, lutr); online_step<false>(s, 0.f, true, m, l, o0, o1, vf); }
;         }
;         const float sc = (l > 0.f) ? g2 / l : 0.f;
; #pragma unroll
;         for (int i = 0; i < 16; ++i) { oa0[i] += sc * o0[i]; oa1[i] += sc * o1[i]; }
.LBB0_1323:
	v_sub_f32_e32 v64, v185, v184
	v_pk_add_f32 v[48:49], v[48:49], v[64:65] op_sel_hi:[1,0] neg_lo:[0,1] neg_hi:[0,1]
	v_pk_add_f32 v[50:51], v[50:51], v[64:65] op_sel_hi:[1,0] neg_lo:[0,1] neg_hi:[0,1]
	v_pk_add_f32 v[52:53], v[52:53], v[64:65] op_sel_hi:[1,0] neg_lo:[0,1] neg_hi:[0,1]
	v_pk_add_f32 v[54:55], v[54:55], v[64:65] op_sel_hi:[1,0] neg_lo:[0,1] neg_hi:[0,1]
	v_pk_add_f32 v[56:57], v[56:57], v[64:65] op_sel_hi:[1,0] neg_lo:[0,1] neg_hi:[0,1]
	v_pk_add_f32 v[58:59], v[58:59], v[64:65] op_sel_hi:[1,0] neg_lo:[0,1] neg_hi:[0,1]
	v_pk_add_f32 v[60:61], v[60:61], v[64:65] op_sel_hi:[1,0] neg_lo:[0,1] neg_hi:[0,1]
	v_pk_add_f32 v[62:63], v[62:63], v[64:65] op_sel_hi:[1,0] neg_lo:[0,1] neg_hi:[0,1]
	v_exp_f32_e32 v48, v48
	v_exp_f32_e32 v49, v49
	v_exp_f32_e32 v50, v50
	v_exp_f32_e32 v51, v51
	v_exp_f32_e32 v52, v52
	v_exp_f32_e32 v53, v53
	v_exp_f32_e32 v54, v54
	v_exp_f32_e32 v55, v55
	v_exp_f32_e32 v56, v56
	v_exp_f32_e32 v57, v57
	v_exp_f32_e32 v58, v58
	v_exp_f32_e32 v59, v59
	v_exp_f32_e32 v60, v60
	v_exp_f32_e32 v61, v61
	v_exp_f32_e32 v62, v62
	v_exp_f32_e32 v63, v63
	v_pk_add_f32 v[64:65], v[48:49], v[50:51]
	v_pk_add_f32 v[66:67], v[52:53], v[54:55]
	v_cvt_pk_bf16_f32 v48, v48, v49
	v_cvt_pk_bf16_f32 v49, v50, v51
	v_cvt_pk_bf16_f32 v50, v52, v53
	v_cvt_pk_bf16_f32 v51, v54, v55
	v_pk_add_f32 v[68:69], v[56:57], v[58:59]
	v_pk_add_f32 v[70:71], v[60:61], v[62:63]
	s_waitcnt vmcnt(3)
	v_mfma_f32_32x32x16_bf16 v[16:31], v[160:163], v[48:51], v[16:31]
	v_pk_add_f32 v[64:65], v[64:65], v[66:67]
	v_pk_add_f32 v[68:69], v[68:69], v[70:71]
	s_waitcnt vmcnt(1)
	v_mfma_f32_32x32x16_bf16 v[32:47], v[156:159], v[48:51], v[32:47]
	v_cvt_pk_bf16_f32 v48, v56, v57
	v_cvt_pk_bf16_f32 v49, v58, v59
	v_cvt_pk_bf16_f32 v50, v60, v61
	v_cvt_pk_bf16_f32 v51, v62, v63
	v_pk_add_f32 v[64:65], v[64:65], v[68:69]
	s_nop 0
	v_mfma_f32_32x32x16_bf16 v[16:31], v[152:155], v[48:51], v[16:31]
	v_add_f32_e32 v63, v64, v65
	v_mov_b32_e32 v64, v63
	s_nop 1
	v_permlane32_swap_b32_e32 v63, v64
	s_waitcnt vmcnt(0)
	v_mfma_f32_32x32x16_bf16 v[32:47], v[148:151], v[48:51], v[32:47]
	v_add_f32_e32 v63, v63, v64
	v_add_f32_e32 v232, v189, v63
	v_mov_b32_e32 v233, v185
.LBB0_1324:
	s_add_i32 s4, s4, 1
	s_sub_i32 s13, s13, 32
	s_add_i32 s6, s6, 32
	s_andn2_b64 vcc, exec, s[8:9]
	v_lshl_add_u64 v[220:221], v[220:221], 0, s[84:85]
	s_cbranch_vccz .LBB0_1326
	s_waitcnt vmcnt(3)
	s_nop 1
	v_mov_b64_e32 v[50:51], v[4:5]
	s_waitcnt vmcnt(2)
	v_mov_b64_e32 v[174:175], v[8:9]
	s_waitcnt vmcnt(1)
	v_mov_b64_e32 v[170:171], v[12:13]
	s_waitcnt vmcnt(0)
	v_mov_b64_e32 v[166:167], v[146:147]
	v_mov_b64_e32 v[48:49], v[2:3]
	v_mov_b64_e32 v[172:173], v[6:7]
	v_mov_b64_e32 v[168:169], v[10:11]
	v_mov_b64_e32 v[164:165], v[144:145]
	v_mov_b32_e32 v189, v232
	v_mov_b32_e32 v185, v233
	s_branch .LBB0_1282
.LBB0_1326:
	s_nop 7
	s_nop 3
	v_mov_b64_e32 v[64:65], v[16:17]
	v_mov_b64_e32 v[66:67], v[18:19]
	v_mov_b64_e32 v[68:69], v[20:21]
	v_mov_b64_e32 v[70:71], v[22:23]
	v_mov_b64_e32 v[72:73], v[24:25]
	v_mov_b64_e32 v[74:75], v[26:27]
	v_mov_b64_e32 v[76:77], v[28:29]
	v_mov_b64_e32 v[78:79], v[30:31]
	v_mov_b64_e32 v[80:81], v[32:33]
	v_mov_b64_e32 v[82:83], v[34:35]
	v_mov_b64_e32 v[84:85], v[36:37]
	v_mov_b64_e32 v[86:87], v[38:39]
	v_mov_b64_e32 v[88:89], v[40:41]
	v_mov_b64_e32 v[90:91], v[42:43]
	v_mov_b64_e32 v[92:93], v[44:45]
	v_mov_b64_e32 v[94:95], v[46:47]
	s_mov_b64 s[6:7], 0
